# v60 + P2 dt task (x.w_dt by MFMA): 12-deep load ring with counted waits instead of 2 loads in flight
# speedup vs baseline: 1.0097x; 1.0097x over previous
; #define MFMA16(a, b, c) __builtin_amdgcn_mfma_f32_16x16x32_bf16((a), (b), (c), 0, 0, 0)
; __device__ __forceinline__ void dt_task(const Params& p, int wt) {
;     const int lane = threadIdx.x & 63, l15 = lane & 15, quad = lane >> 4, r0 = wt * 16;
;     const bfu* xb = (const bfu*)(p.ws + WS_XB) + (size_t)(r0 + l15) * 1024 + quad * 8;
;     const bfu* wd = (const bfu*)(p.ws + WS_WDT) + (size_t)l15 * 1024 + quad * 8;
;     f32x4 acc = {0.f, 0.f, 0.f, 0.f};
; #pragma unroll 8
;     for (int ks = 0; ks < 32; ++ks) acc = MFMA16(ld8g(xb + ks * 32), ld8g(wd + ks * 32), acc);
;     float* dt = (float*)(p.ws + WS_DT);
;     const float bias = p.dt_bias[l15];
; #pragma unroll
;     for (int j = 0; j < 4; ++j) { const float v = acc[j] + bias; dt[(size_t)(r0 + quad * 4 + j) * 16 + l15] = (v > 20.f) ? v : log1pf(__expf(v)); }
.LBB0_243:
	v_add_co_u32_e32 v46, vcc, 0x2200000, v6
	s_nop 1
	v_addc_co_u32_e32 v47, vcc, 0, v7, vcc
	v_add_co_u32_e32 v48, vcc, 0xc00000, v4
	s_nop 1
	v_addc_co_u32_e32 v49, vcc, 0, v5, vcc
	global_load_dwordx4 v[124:127], v[46:47], off
	global_load_dwordx4 v[128:131], v[48:49], off
	global_load_dwordx4 v[132:135], v[46:47], off offset:64
	global_load_dwordx4 v[136:139], v[48:49], off offset:64
	global_load_dwordx4 v[140:143], v[46:47], off offset:128
	global_load_dwordx4 v[144:147], v[48:49], off offset:128
	global_load_dwordx4 v[148:151], v[46:47], off offset:192
	global_load_dwordx4 v[152:155], v[48:49], off offset:192
	global_load_dwordx4 v[156:159], v[46:47], off offset:256
	global_load_dwordx4 v[160:163], v[48:49], off offset:256
	global_load_dwordx4 v[164:167], v[46:47], off offset:320
	global_load_dwordx4 v[168:171], v[48:49], off offset:320
	global_load_dwordx4 v[196:199], v[46:47], off offset:384
	global_load_dwordx4 v[200:203], v[48:49], off offset:384
	global_load_dwordx4 v[204:207], v[46:47], off offset:448
	global_load_dwordx4 v[208:211], v[48:49], off offset:448
	global_load_dwordx4 v[212:215], v[46:47], off offset:512
	global_load_dwordx4 v[216:219], v[48:49], off offset:512
	global_load_dwordx4 v[220:223], v[46:47], off offset:576
	global_load_dwordx4 v[224:227], v[48:49], off offset:576
	global_load_dwordx4 v[228:231], v[46:47], off offset:640
	global_load_dwordx4 v[232:235], v[48:49], off offset:640
	global_load_dwordx4 v[236:239], v[46:47], off offset:704
	global_load_dwordx4 v[240:243], v[48:49], off offset:704
	s_waitcnt vmcnt(22)
	v_mfma_f32_16x16x32_bf16 v[0:3], v[124:127], v[128:131], v[0:3]
	global_load_dwordx4 v[124:127], v[46:47], off offset:768
	global_load_dwordx4 v[128:131], v[48:49], off offset:768
	s_waitcnt vmcnt(22)
	v_mfma_f32_16x16x32_bf16 v[0:3], v[132:135], v[136:139], v[0:3]
	global_load_dwordx4 v[132:135], v[46:47], off offset:832
	global_load_dwordx4 v[136:139], v[48:49], off offset:832
	s_waitcnt vmcnt(22)
	v_mfma_f32_16x16x32_bf16 v[0:3], v[140:143], v[144:147], v[0:3]
	global_load_dwordx4 v[140:143], v[46:47], off offset:896
	global_load_dwordx4 v[144:147], v[48:49], off offset:896
	s_waitcnt vmcnt(22)
	v_mfma_f32_16x16x32_bf16 v[0:3], v[148:151], v[152:155], v[0:3]
	global_load_dwordx4 v[148:151], v[46:47], off offset:960
	global_load_dwordx4 v[152:155], v[48:49], off offset:960
	s_waitcnt vmcnt(22)
	v_mfma_f32_16x16x32_bf16 v[0:3], v[156:159], v[160:163], v[0:3]
	global_load_dwordx4 v[156:159], v[46:47], off offset:1024
	global_load_dwordx4 v[160:163], v[48:49], off offset:1024
	s_waitcnt vmcnt(22)
	v_mfma_f32_16x16x32_bf16 v[0:3], v[164:167], v[168:171], v[0:3]
	global_load_dwordx4 v[164:167], v[46:47], off offset:1088
	global_load_dwordx4 v[168:171], v[48:49], off offset:1088
	s_waitcnt vmcnt(22)
	v_mfma_f32_16x16x32_bf16 v[0:3], v[196:199], v[200:203], v[0:3]
	global_load_dwordx4 v[196:199], v[46:47], off offset:1152
	global_load_dwordx4 v[200:203], v[48:49], off offset:1152
	s_waitcnt vmcnt(22)
	v_mfma_f32_16x16x32_bf16 v[0:3], v[204:207], v[208:211], v[0:3]
	global_load_dwordx4 v[204:207], v[46:47], off offset:1216
	global_load_dwordx4 v[208:211], v[48:49], off offset:1216
	s_waitcnt vmcnt(22)
	v_mfma_f32_16x16x32_bf16 v[0:3], v[212:215], v[216:219], v[0:3]
	global_load_dwordx4 v[212:215], v[46:47], off offset:1280
	global_load_dwordx4 v[216:219], v[48:49], off offset:1280
	s_waitcnt vmcnt(22)
	v_mfma_f32_16x16x32_bf16 v[0:3], v[220:223], v[224:227], v[0:3]
	global_load_dwordx4 v[220:223], v[46:47], off offset:1344
	global_load_dwordx4 v[224:227], v[48:49], off offset:1344
	s_waitcnt vmcnt(22)
	v_mfma_f32_16x16x32_bf16 v[0:3], v[228:231], v[232:235], v[0:3]
	global_load_dwordx4 v[228:231], v[46:47], off offset:1408
	global_load_dwordx4 v[232:235], v[48:49], off offset:1408
	s_waitcnt vmcnt(22)
	v_mfma_f32_16x16x32_bf16 v[0:3], v[236:239], v[240:243], v[0:3]
	global_load_dwordx4 v[236:239], v[46:47], off offset:1472
	global_load_dwordx4 v[240:243], v[48:49], off offset:1472
	s_waitcnt vmcnt(22)
	v_mfma_f32_16x16x32_bf16 v[0:3], v[124:127], v[128:131], v[0:3]
	global_load_dwordx4 v[124:127], v[46:47], off offset:1536
	global_load_dwordx4 v[128:131], v[48:49], off offset:1536
	s_waitcnt vmcnt(22)
	v_mfma_f32_16x16x32_bf16 v[0:3], v[132:135], v[136:139], v[0:3]
	global_load_dwordx4 v[132:135], v[46:47], off offset:1600
	global_load_dwordx4 v[136:139], v[48:49], off offset:1600
	s_waitcnt vmcnt(22)
	v_mfma_f32_16x16x32_bf16 v[0:3], v[140:143], v[144:147], v[0:3]
	global_load_dwordx4 v[140:143], v[46:47], off offset:1664
	global_load_dwordx4 v[144:147], v[48:49], off offset:1664
	s_waitcnt vmcnt(22)
	v_mfma_f32_16x16x32_bf16 v[0:3], v[148:151], v[152:155], v[0:3]
	global_load_dwordx4 v[148:151], v[46:47], off offset:1728
	global_load_dwordx4 v[152:155], v[48:49], off offset:1728
	s_waitcnt vmcnt(22)
	v_mfma_f32_16x16x32_bf16 v[0:3], v[156:159], v[160:163], v[0:3]
	global_load_dwordx4 v[156:159], v[46:47], off offset:1792
	global_load_dwordx4 v[160:163], v[48:49], off offset:1792
	s_waitcnt vmcnt(22)
	v_mfma_f32_16x16x32_bf16 v[0:3], v[164:167], v[168:171], v[0:3]
	global_load_dwordx4 v[164:167], v[46:47], off offset:1856
	global_load_dwordx4 v[168:171], v[48:49], off offset:1856
	s_waitcnt vmcnt(22)
	v_mfma_f32_16x16x32_bf16 v[0:3], v[196:199], v[200:203], v[0:3]
	global_load_dwordx4 v[196:199], v[46:47], off offset:1920
	global_load_dwordx4 v[200:203], v[48:49], off offset:1920
	s_waitcnt vmcnt(22)
	v_mfma_f32_16x16x32_bf16 v[0:3], v[204:207], v[208:211], v[0:3]
	global_load_dwordx4 v[204:207], v[46:47], off offset:1984
	global_load_dwordx4 v[208:211], v[48:49], off offset:1984
	s_waitcnt vmcnt(22)
	v_mfma_f32_16x16x32_bf16 v[0:3], v[212:215], v[216:219], v[0:3]
	s_waitcnt vmcnt(20)
	v_mfma_f32_16x16x32_bf16 v[0:3], v[220:223], v[224:227], v[0:3]
	s_waitcnt vmcnt(18)
	v_mfma_f32_16x16x32_bf16 v[0:3], v[228:231], v[232:235], v[0:3]
	s_waitcnt vmcnt(16)
	v_mfma_f32_16x16x32_bf16 v[0:3], v[236:239], v[240:243], v[0:3]
	s_waitcnt vmcnt(14)
	v_mfma_f32_16x16x32_bf16 v[0:3], v[124:127], v[128:131], v[0:3]
	s_waitcnt vmcnt(12)
	v_mfma_f32_16x16x32_bf16 v[0:3], v[132:135], v[136:139], v[0:3]
	s_waitcnt vmcnt(10)
	v_mfma_f32_16x16x32_bf16 v[0:3], v[140:143], v[144:147], v[0:3]
	s_waitcnt vmcnt(8)
	v_mfma_f32_16x16x32_bf16 v[0:3], v[148:151], v[152:155], v[0:3]
	s_waitcnt vmcnt(6)
	v_mfma_f32_16x16x32_bf16 v[0:3], v[156:159], v[160:163], v[0:3]
	s_waitcnt vmcnt(4)
	v_mfma_f32_16x16x32_bf16 v[0:3], v[164:167], v[168:171], v[0:3]
	s_waitcnt vmcnt(2)
	v_mfma_f32_16x16x32_bf16 v[0:3], v[196:199], v[200:203], v[0:3]
	s_waitcnt vmcnt(0)
	v_mfma_f32_16x16x32_bf16 v[0:3], v[204:207], v[208:211], v[0:3]
	global_load_dword v6, v118, s[38:39]
	s_waitcnt vmcnt(0)
	s_nop 4
	v_add_f32_e32 v0, v0, v6
	v_cmp_nlt_f32_e32 vcc, s41, v0
	s_and_saveexec_b64 s[38:39], vcc
	s_cbranch_execz .LBB0_246
; __device__ __forceinline__ void dt_task(const Params& p, int wt) {
;     ...
;     for (int j = 0; j < 4; ++j) { const float v = acc[j] + bias; dt[(size_t)(r0 + quad * 4 + j) * 16 + l15] = (v > 20.f) ? v : log1pf(__expf(v)); }
	v_mul_f32_e32 v0, 0x3fb8aa3b, v0
	v_exp_f32_e32 v0, v0
	s_nop 0
	v_add_f32_e32 v7, 1.0, v0
	v_frexp_mant_f32_e32 v10, v7
	v_cvt_f64_f32_e32 v[4:5], v7
	v_frexp_exp_i32_f64_e32 v4, v[4:5]
	v_cmp_gt_f32_e32 vcc, s44, v10
	v_add_f32_e32 v9, -1.0, v7
	v_sub_f32_e32 v11, v9, v7
	v_subbrev_co_u32_e32 v16, vcc, 0, v4, vcc
	v_sub_u32_e32 v4, 0, v16
	v_sub_f32_e32 v9, v0, v9
	v_add_f32_e32 v11, 1.0, v11
	v_ldexp_f32 v5, v7, v4
	v_add_f32_e32 v9, v9, v11
	v_add_f32_e32 v7, -1.0, v5
	v_add_f32_e32 v10, 1.0, v5
	v_ldexp_f32 v4, v9, v4
	v_add_f32_e32 v9, 1.0, v7
	v_add_f32_e32 v11, -1.0, v10
	v_sub_f32_e32 v9, v5, v9
	v_sub_f32_e32 v5, v5, v11
	v_add_f32_e32 v9, v4, v9
	v_add_f32_e32 v4, v4, v5
	v_add_f32_e32 v17, v10, v4
	v_rcp_f32_e32 v19, v17
	v_sub_f32_e32 v5, v17, v10
	v_sub_f32_e32 v18, v4, v5
	v_add_f32_e32 v5, v7, v9
	v_sub_f32_e32 v4, v5, v7
	v_sub_f32_e32 v7, v9, v4
	v_mul_f32_e32 v9, v5, v19
	v_mul_f32_e32 v10, v17, v9
	v_fma_f32 v12, v9, v17, -v10
	v_fmac_f32_e32 v12, v9, v18
	v_add_f32_e32 v4, v10, v12
	v_sub_f32_e32 v11, v5, v4
	v_pk_add_f32 v[14:15], v[4:5], v[10:11] neg_lo:[0,1] neg_hi:[0,1]
	v_mov_b32_e32 v13, v4
	v_pk_add_f32 v[4:5], v[14:15], v[12:13] neg_lo:[0,1] neg_hi:[0,1]
	v_cmp_neq_f32_e32 vcc, s46, v0
	v_add_f32_e32 v5, v7, v5
	v_add_f32_e32 v4, v4, v5
	v_add_f32_e32 v5, v11, v4
	v_mul_f32_e32 v7, v19, v5
	v_mul_f32_e32 v10, v17, v7
	v_fma_f32 v12, v7, v17, -v10
	v_fmac_f32_e32 v12, v7, v18
	v_sub_f32_e32 v11, v11, v5
	v_add_f32_e32 v17, v4, v11
	v_add_f32_e32 v4, v10, v12
	v_sub_f32_e32 v11, v5, v4
	v_pk_add_f32 v[14:15], v[4:5], v[10:11] neg_lo:[0,1] neg_hi:[0,1]
	v_mov_b32_e32 v13, v4
	v_pk_add_f32 v[4:5], v[14:15], v[12:13] neg_lo:[0,1] neg_hi:[0,1]
	s_nop 0
	v_add_f32_e32 v5, v17, v5
	v_add_f32_e32 v4, v4, v5
	v_add_f32_e32 v5, v9, v7
	v_add_f32_e32 v4, v11, v4
	v_sub_f32_e32 v9, v5, v9
	v_mul_f32_e32 v4, v19, v4
	v_sub_f32_e32 v7, v7, v9
	v_add_f32_e32 v7, v7, v4
	v_add_f32_e32 v9, v5, v7
	v_mul_f32_e32 v10, v9, v9
	v_fmamk_f32 v4, v10, 0x3e9b6dac, v119
	v_fmaak_f32 v87, v10, v4, 0x3f2aaada
	v_cvt_f32_i32_e32 v4, v16
	v_sub_f32_e32 v5, v9, v5
	v_sub_f32_e32 v5, v7, v5
	v_ldexp_f32 v7, v5, 1
	v_mul_f32_e32 v5, v9, v10
	v_pk_mul_f32 v[12:13], v[4:5], v[86:87]
	v_ldexp_f32 v11, v9, 1
	v_fma_f32 v10, v4, s45, -v12
	v_fmac_f32_e32 v10, 0xb102e308, v4
	v_pk_add_f32 v[4:5], v[12:13], v[10:11]
	v_mov_b32_e32 v14, v12
	v_sub_f32_e32 v9, v5, v11
	v_sub_f32_e32 v9, v13, v9
	v_add_f32_e32 v15, v7, v9
	v_pk_add_f32 v[12:13], v[4:5], v[12:13] neg_lo:[0,1] neg_hi:[0,1]
	v_pk_add_f32 v[16:17], v[4:5], v[14:15]
	v_mov_b32_e32 v11, v4
	v_mov_b32_e32 v13, v17
	v_pk_add_f32 v[18:19], v[10:11], v[12:13] neg_lo:[0,1] neg_hi:[0,1]
	v_pk_add_f32 v[10:11], v[10:11], v[12:13]
	v_mov_b32_e32 v14, v15
	v_pk_add_f32 v[12:13], v[10:11], v[4:5] op_sel:[1,0] op_sel_hi:[0,1] neg_lo:[0,1] neg_hi:[0,1]
	v_pk_add_f32 v[20:21], v[16:17], v[12:13] op_sel_hi:[1,0] neg_lo:[0,1] neg_hi:[0,1]
	v_mov_b32_e32 v16, v17
	v_mov_b32_e32 v17, v11
	v_pk_mov_b32 v[12:13], v[4:5], v[12:13] op_sel:[1,0]
	v_mov_b32_e32 v15, v4
	v_pk_add_f32 v[12:13], v[16:17], v[12:13] neg_lo:[0,1] neg_hi:[0,1]
	v_mov_b32_e32 v20, v18
	v_pk_add_f32 v[4:5], v[14:15], v[12:13] neg_lo:[0,1] neg_hi:[0,1]
	v_mov_b32_e32 v19, v11
	v_pk_add_f32 v[12:13], v[20:21], v[4:5]
	s_nop 0
	v_pk_add_f32 v[14:15], v[12:13], v[12:13] op_sel:[0,1] op_sel_hi:[1,0]
	s_nop 0
	v_pk_add_f32 v[10:11], v[10:11], v[14:15] op_sel:[1,0] op_sel_hi:[0,1]
	v_mov_b32_e32 v13, v10
	v_pk_add_f32 v[16:17], v[12:13], v[18:19] neg_lo:[0,1] neg_hi:[0,1]
	v_mov_b32_e32 v5, v14
	v_sub_f32_e32 v7, v12, v16
	v_pk_add_f32 v[4:5], v[4:5], v[16:17] neg_lo:[0,1] neg_hi:[0,1]
	v_sub_f32_e32 v7, v18, v7
	v_add_f32_e32 v4, v4, v7
	v_add_f32_e32 v4, v4, v5
	v_add_f32_e32 v4, v10, v4
	v_cndmask_b32_e32 v4, v120, v4, vcc
	v_cmp_ngt_f32_e32 vcc, -1.0, v0
	s_nop 1
	v_cndmask_b32_e32 v4, v121, v4, vcc
	v_cmp_neq_f32_e32 vcc, -1.0, v0
	s_nop 1
	v_cndmask_b32_e32 v4, v122, v4, vcc
	v_cmp_lt_f32_e64 vcc, |v0|, s47
	s_nop 1
	v_cndmask_b32_e32 v0, v4, v0, vcc
